# speedup vs baseline: 1.0046x; 1.0046x over previous
; #define STAGE_A(P, half, kt) do { const char* _p = Ab + (half) * aH + (long)(kt) * (BK * 2);                           \
;     __builtin_amdgcn_global_load_lds((const unsigned*)(_p + voA), (unsigned*)((char*)(P) + wid * 1024), 16, 0, 0);         \
;     __builtin_amdgcn_global_load_lds((const unsigned*)(_p + a64 + voA), (unsigned*)((char*)(P) + wid * 1024 + 8192), 16, 0, 0); } while (0)
; #define STAGE_B(P, half, kt) do { const char* _p = Bb + (half) * bH + (long)(kt) * (BK * 2);                           \
;     __builtin_amdgcn_global_load_lds((const unsigned*)(_p + voB), (unsigned*)((char*)(P) + wid * 1024), 16, 0, 0);         \
;     __builtin_amdgcn_global_load_lds((const unsigned*)(_p + b64 + voB), (unsigned*)((char*)(P) + wid * 1024 + 8192), 16, 0, 0); } while (0)
; #define WAIT_V(n) asm volatile("s_waitcnt vmcnt(" #n ")" ::: "memory")
; #define BAR __builtin_amdgcn_s_barrier()
; __device__ __forceinline__ void gemm_tile(const GemmArgs& g, bf16* shm, const int tid, const int wid, char* wsb, const float* gnext) {
;     ...
;   STAGE_B(SB(0, 0), 0, 0); STAGE_A(SA(0, 0), 0, 0);
;   STAGE_B(SB(0, 1), 1, 0); STAGE_A(SA(0, 1), 1, 0);
;   if (wr == 1) BAR;
;   WAIT_V(4); BAR;
.Ltile_join:
	s_mov_b32 m0, s75
	s_barrier
	s_waitcnt vmcnt(0)
	v_readfirstlane_b32 s10, v6
	s_waitcnt vmcnt(2)
	v_readfirstlane_b32 s2, v8
	v_readfirstlane_b32 s16, v9
	s_ashr_i32 s3, s2, 31
	s_ashr_i32 s17, s16, 31
	s_lshl_b64 s[6:7], s[2:3], 7
	s_lshl_b64 s[14:15], s[16:17], 7
	v_readfirstlane_b32 s11, v7
	s_add_u32 s28, s10, s14
	v_readfirstlane_b32 s0, v4
	s_addc_u32 s29, s11, s15
	s_add_i32 s77, s26, 0x12000
	v_readfirstlane_b32 s1, v5
	s_add_u32 s66, s0, s6
	s_addc_u32 s67, s1, s7
	s_add_i32 s84, s26, 0x2000
	v_mul_lo_u32 v1, s16, v145
	s_add_u32 s48, s28, s14
	s_waitcnt lgkmcnt(0)
	v_add_lshl_u32 v2, v1, v150, 1
	s_addc_u32 s49, s29, s15
	s_add_i32 s85, s26, 0x14000
	v_mul_lo_u32 v0, s2, v145
	global_load_lds_dwordx4 v2, s[10:11]
	s_mov_b32 m0, s77
	s_add_u32 s50, s48, s14
	v_add_lshl_u32 v0, v0, v150, 1
	global_load_lds_dwordx4 v2, s[28:29]
	s_mov_b32 m0, s26
	s_addc_u32 s51, s49, s15
	s_add_i32 s86, s26, 0x16000
	global_load_lds_dwordx4 v0, s[0:1]
	s_mov_b32 m0, s84
	s_add_u32 s72, s66, s6
	global_load_lds_dwordx4 v0, s[66:67]
	s_mov_b32 m0, s85
	s_addc_u32 s73, s67, s7
	s_add_i32 s87, s26, 0x4000
	global_load_lds_dwordx4 v2, s[48:49]
	s_mov_b32 m0, s86
	s_add_u32 s28, s72, s6
	global_load_lds_dwordx4 v2, s[50:51]
	s_mov_b32 m0, s87
	s_addc_u32 s29, s73, s7
	s_add_i32 s88, s26, 0x6000
	global_load_lds_dwordx4 v0, s[72:73]
	s_mov_b32 m0, s88
	s_waitcnt vmcnt(7)
	v_readfirstlane_b32 s69, v17
	global_load_lds_dwordx4 v0, s[28:29]
	v_readlane_b32 s28, v255, 7
	v_readlane_b32 s29, v255, 8
	v_readfirstlane_b32 s68, v16
	v_readfirstlane_b32 s71, v19
	v_readfirstlane_b32 s70, v18
	v_readfirstlane_b32 s66, v10
	v_readfirstlane_b32 s67, v11
	v_readfirstlane_b32 s89, v12
	v_readfirstlane_b32 s9, v13
	v_readfirstlane_b32 s74, v14
	s_andn2_b64 vcc, exec, s[28:29]
	v_readfirstlane_b32 s83, v15
	s_cbranch_vccnz .LBB0_37
	s_barrier

.LBB0_170:
	v_add_f32_e32 v1, 0, v24
	v_add_f32_e32 v1, v25, v1
	v_add_f32_e32 v1, v26, v1
	v_add_f32_e32 v1, v27, v1
	v_add_f32_e32 v1, v28, v1
	v_add_f32_e32 v1, v29, v1
	v_add_f32_e32 v1, v30, v1
	v_add_f32_e32 v1, v31, v1
	v_add_f32_e32 v1, v32, v1
	v_add_f32_e32 v1, v33, v1
	v_add_f32_e32 v1, v34, v1
	v_add_f32_e32 v1, v35, v1
	v_add_f32_e32 v1, v36, v1
	v_add_f32_e32 v1, v37, v1
	s_waitcnt lgkmcnt(4)
	v_add_f32_e32 v1, v38, v1
	v_add_f32_e32 v1, v39, v1
	v_sub_f32_e32 v0, v0, v203
	v_add_f32_e32 v1, 0, v1
	v_add_u32_e32 v2, 0x24000, v179
	v_mul_f32_e32 v0, 0x3e0293ee, v0
	v_mfma_f32_32x32x16_bf16 v[32:47], v[8:11], v[16:19], 0
	ds_read_b64_tr_b16 v[132:133], v180 offset:0x1000
	v_fmamk_f32 v52, v78, 0x3e0293ee, v0
	ds_read_b64_tr_b16 v[134:135], v180 offset:0x1800
	v_exp_f32_e32 v94, v52
	v_fmamk_f32 v53, v79, 0x3e0293ee, v0
	ds_read_b64_tr_b16 v[136:137], v180 offset:0x1200
	v_exp_f32_e32 v95, v53
	v_mfma_f32_32x32x16_bf16 v[16:31], v[8:11], v[20:23], 0
	ds_read_b64_tr_b16 v[138:139], v180 offset:0x1a00
	s_waitcnt lgkmcnt(4)
	v_add_f32_e32 v52, 0, v94
	v_add_f32_e32 v140, v95, v52
	v_mfma_f32_32x32x16_bf16 v[64:79], v[8:11], v[12:15], 0
	v_mfma_f32_32x32x16_bf16 v[48:63], v[8:11], v[48:51], 0
	v_fmamk_f32 v8, v80, 0x3e0293ee, v0
	v_exp_f32_e32 v158, v8
	v_fmamk_f32 v9, v81, 0x3e0293ee, v0
	v_exp_f32_e32 v159, v9
	v_add_f32_e32 v8, v158, v140
	v_add_f32_e32 v80, v159, v8
	ds_read_b128 v[8:11], v202 offset:0x800
	ds_read_b64_tr_b16 v[12:13], v180 offset:0x1400
	ds_read_b64_tr_b16 v[14:15], v180 offset:0x1c00
	ds_read_b64_tr_b16 v[140:141], v180 offset:0x1600
	ds_read_b64_tr_b16 v[142:143], v180 offset:0x1e00
	s_waitcnt lgkmcnt(5)
	v_fmamk_f32 v81, v82, 0x3e0293ee, v0
	v_exp_f32_e32 v160, v81
	v_fmamk_f32 v81, v83, 0x3e0293ee, v0
	v_exp_f32_e32 v161, v81
	v_mfma_f32_32x32x16_bf16 v[32:47], v[4:7], v[132:135], v[32:47]
	v_add_f32_e32 v80, v160, v80
	v_mfma_f32_32x32x16_bf16 v[16:31], v[4:7], v[136:139], v[16:31]
	v_add_f32_e32 v136, v161, v80
	ds_read_b64_tr_b16 v[80:81], v180 offset:0x2000
	ds_read_b64_tr_b16 v[82:83], v180 offset:0x2800
	ds_read_b64_tr_b16 v[132:133], v180 offset:0x2200
	ds_read_b64_tr_b16 v[134:135], v180 offset:0x2a00
	s_waitcnt lgkmcnt(4)
	v_mfma_f32_32x32x16_bf16 v[64:79], v[4:7], v[12:15], v[64:79]
	v_mfma_f32_32x32x16_bf16 v[48:63], v[4:7], v[140:143], v[48:63]
	v_fmamk_f32 v4, v84, 0x3e0293ee, v0
	v_exp_f32_e32 v140, v4
	v_fmamk_f32 v5, v85, 0x3e0293ee, v0
	v_exp_f32_e32 v141, v5
	v_add_f32_e32 v4, v140, v136
	v_add_f32_e32 v84, v141, v4
	ds_read_b128 v[4:7], v202 offset:0xc00
	ds_read_b64_tr_b16 v[12:13], v180 offset:0x2400
	ds_read_b64_tr_b16 v[14:15], v180 offset:0x2c00
	ds_read_b64_tr_b16 v[136:137], v180 offset:0x2600
	ds_read_b64_tr_b16 v[138:139], v180 offset:0x2e00
	s_waitcnt lgkmcnt(5)
	v_mfma_f32_32x32x16_bf16 v[32:47], v[8:11], v[80:83], v[32:47]
	v_fmamk_f32 v80, v86, 0x3e0293ee, v0
	v_fmamk_f32 v81, v87, 0x3e0293ee, v0
	v_mfma_f32_32x32x16_bf16 v[16:31], v[8:11], v[132:135], v[16:31]
	v_exp_f32_e32 v132, v80
	v_exp_f32_e32 v133, v81
	v_add_f32_e32 v80, v132, v84
	v_add_f32_e32 v134, v133, v80
	ds_read_b64_tr_b16 v[80:81], v180 offset:0x3000
	ds_read_b64_tr_b16 v[82:83], v180 offset:0x3800
	ds_read_b64_tr_b16 v[84:85], v180 offset:0x3200
	ds_read_b64_tr_b16 v[86:87], v180 offset:0x3a00
	s_waitcnt lgkmcnt(4)
	v_mfma_f32_32x32x16_bf16 v[64:79], v[8:11], v[12:15], v[64:79]
	v_mfma_f32_32x32x16_bf16 v[48:63], v[8:11], v[136:139], v[48:63]
	v_fmamk_f32 v8, v88, 0x3e0293ee, v0
	v_exp_f32_e32 v88, v8
	v_fmamk_f32 v9, v89, 0x3e0293ee, v0
	v_exp_f32_e32 v89, v9
	v_add_f32_e32 v8, v88, v134
	v_add_f32_e32 v134, v89, v8
	ds_read_b64_tr_b16 v[8:9], v180 offset:0x3400
	ds_read_b64_tr_b16 v[10:11], v180 offset:0x3c00
	ds_read_b64_tr_b16 v[12:13], v180 offset:0x3600
	ds_read_b64_tr_b16 v[14:15], v180 offset:0x3e00
	s_waitcnt lgkmcnt(4)
	v_mfma_f32_32x32x16_bf16 v[32:47], v[4:7], v[80:83], v[32:47]
	v_fmamk_f32 v80, v90, 0x3e0293ee, v0
	v_exp_f32_e32 v80, v80
	v_fmamk_f32 v81, v91, 0x3e0293ee, v0
	v_exp_f32_e32 v81, v81
	s_waitcnt lgkmcnt(0)
	v_add_f32_e32 v82, v80, v134
	v_add_f32_e32 v82, v81, v82
	v_mfma_f32_32x32x16_bf16 v[16:31], v[4:7], v[84:87], v[16:31]
	v_mfma_f32_32x32x16_bf16 v[64:79], v[4:7], v[8:11], v[64:79]
	v_add_u32_e32 v205, s28, v2
	s_mov_b32 s0, 0x8000
	s_andn2_b64 vcc, exec, s[2:3]
	v_mfma_f32_32x32x16_bf16 v[48:63], v[4:7], v[12:15], v[48:63]
	v_fmamk_f32 v4, v92, 0x3e0293ee, v0
	v_exp_f32_e32 v8, v4
	v_fmac_f32_e32 v0, 0x3e0293ee, v93
	v_exp_f32_e32 v0, v0
	v_add_f32_e32 v4, v8, v82
	v_add_f32_e32 v4, v0, v4
	v_add_f32_e32 v207, v1, v4
	v_cvt_pk_bf16_f32 v4, v94, v95
	v_cvt_pk_bf16_f32 v5, v158, v159
	v_cvt_pk_bf16_f32 v6, v160, v161
	v_cvt_pk_bf16_f32 v7, v140, v141
	s_nop 0
	v_permlane32_swap_b32_e32 v4, v6
	v_permlane32_swap_b32_e32 v5, v7
	ds_write_b128 v205, v[4:7]
	v_cvt_pk_bf16_f32 v4, v132, v133
	v_cvt_pk_bf16_f32 v5, v88, v89
	v_cvt_pk_bf16_f32 v6, v80, v81
	v_cvt_pk_bf16_f32 v7, v8, v0
	s_nop 0
	v_permlane32_swap_b32_e32 v4, v6
	v_permlane32_swap_b32_e32 v5, v7
	ds_write_b128 v205, v[4:7] offset:1024
	s_waitcnt vmcnt(0)
	s_waitcnt vmcnt(0) lgkmcnt(0)
	s_barrier
	s_cbranch_vccnz .LBB0_188
	v_xor_b32_e32 v158, 0x80000000, v148
	v_add_u32_e32 v206, 0x4000, v202
	v_mov_b32_e32 v160, v158
	v_mov_b32_e32 v161, v158
	s_mov_b32 s88, 0
	s_mov_b32 s29, 2
	s_mov_b32 s0, 1
	s_movk_i32 s89, 0x100
	s_mov_b32 s90, 4
	s_lshl_b32 s98, s80, 6
	s_sub_i32 s96, s89, 64
	s_sub_i32 s98, s98, 64
	s_min_i32 s96, s96, s98
	s_mul_i32 s96, s96, 0x6000
	s_lshl_b32 s97, s88, 15
	s_add_i32 s97, s83, s97
	v_add_u32_e32 v242, s96, v150
	v_add_u32_e32 v243, s96, v154
	v_add_u32_e32 v244, s96, v152
	v_add_u32_e32 v245, s96, v156
	v_add_u32_e32 v246, 0x100, v244
	v_add_u32_e32 v247, 0x100, v245
	s_branch .Lattn_head

.Lattn_head:
.LBB0_174:
	ds_read_b128 v[8:11], v206 offset:0
	s_add_i32 s91, s82, s89
	v_lshl_add_u32 v208, s0, 15, v180
	ds_read_b128 v[4:7], v206 offset:0x400
	s_add_i32 s28, s89, 0xffffff80
	s_add_i32 s2, s91, 0xffffff80
	s_add_i32 s0, s91, 0xffffff9f
	ds_read_b64_tr_b16 v[136:137], v208 offset:0
	s_cmp_gt_i32 s0, s86
	ds_read_b64_tr_b16 v[138:139], v208 offset:0x800
	s_cselect_b64 s[8:9], -1, 0
	s_cmp_lt_i32 s2, s87
	ds_read_b64_tr_b16 v[140:141], v208 offset:0x200
	s_cselect_b64 s[0:1], -1, 0
	s_cmp_ge_i32 s2, s87
	ds_read_b64_tr_b16 v[142:143], v208 offset:0xa00
	s_cselect_b64 s[2:3], -1, 0
	ds_read_b64_tr_b16 v[12:13], v208 offset:0x400
	s_and_b64 vcc, s[8:9], s[2:3]
	ds_read_b64_tr_b16 v[14:15], v208 offset:0xc00
	v_cndmask_b32_e32 v0, 0, v183, vcc
	v_cndmask_b32_e32 v1, 0, v184, vcc
	ds_read_b64_tr_b16 v[132:133], v208 offset:0x600
	v_cndmask_b32_e64 v0, v181, v0, s[8:9]
	v_cndmask_b32_e64 v1, v182, v1, s[8:9]
	v_mov_b32_e32 v2, v3
	ds_read_b64_tr_b16 v[134:135], v208 offset:0xe00
	ds_read_b128 v[210:213], v186 offset:0
	ds_read_b128 v[214:217], v187 offset:0
	ds_read_b128 v[218:221], v188 offset:0
	ds_read_b128 v[222:225], v189 offset:0
	s_nop 1
	v_mfma_f32_32x32x16_bf16 v[80:95], v[128:131], v[0:3], 0
	s_add_i32 m0, s83, 0x1c000
	s_nop 0
	global_load_lds_dwordx4 v242, s[74:75]
	s_waitcnt lgkmcnt(3)
	v_mfma_f32_32x32x16_bf16 v[80:95], v[210:213], v[96:99], v[80:95]
	ds_read_b128 v[210:213], v186 offset:0x80
	s_add_i32 m0, s83, 0x1c400
	s_nop 0
	global_load_lds_dwordx4 v243, s[74:75]
	s_waitcnt lgkmcnt(3)
	v_mfma_f32_32x32x16_bf16 v[80:95], v[214:217], v[100:103], v[80:95]
	ds_read_b128 v[214:217], v187 offset:0x80
	s_waitcnt lgkmcnt(3)
	v_mfma_f32_32x32x16_bf16 v[80:95], v[218:221], v[104:107], v[80:95]
	ds_read_b128 v[218:221], v188 offset:0x80
	s_waitcnt lgkmcnt(3)
	v_mfma_f32_32x32x16_bf16 v[80:95], v[222:225], v[108:111], v[80:95]
	ds_read_b128 v[222:225], v189 offset:0x80
	s_waitcnt lgkmcnt(3)
	v_mfma_f32_32x32x16_bf16 v[80:95], v[210:213], v[112:115], v[80:95]
	s_waitcnt lgkmcnt(2)
	v_mfma_f32_32x32x16_bf16 v[80:95], v[214:217], v[116:119], v[80:95]
	s_waitcnt lgkmcnt(1)
	v_mfma_f32_32x32x16_bf16 v[80:95], v[218:221], v[120:123], v[80:95]
	s_waitcnt lgkmcnt(0)
	v_mfma_f32_32x32x16_bf16 v[80:95], v[222:225], v[124:127], v[80:95]
	v_cvt_f32_u32_e32 v0, s28
	s_and_b64 s[2:3], s[8:9], s[0:1]
	s_mov_b64 s[0:1], -1
	s_andn2_b64 vcc, exec, s[2:3]
	v_sub_f32_e32 v1, v185, v0
	s_cbranch_vccz .LBB0_176
	v_cndmask_b32_e64 v0, -v148, v148, s[8:9]
	v_mul_f32_e32 v0, v1, v0
	s_mov_b64 s[0:1], 0

.LBB0_178:
	v_sub_f32_e32 v0, v0, v203
	v_mul_f32_e32 v0, 0x3e0293ee, v0
	s_waitcnt lgkmcnt(4)
	v_mfma_f32_32x32x16_bf16 v[32:47], v[8:11], v[136:139], v[32:47]
	ds_read_b64_tr_b16 v[136:137], v208 offset:0x1000
	ds_read_b64_tr_b16 v[138:139], v208 offset:0x1800
	v_fmamk_f32 v1, v80, 0x3e0293ee, v0
	v_exp_f32_e32 v209, v1
	v_mfma_f32_32x32x16_bf16 v[16:31], v[8:11], v[140:143], v[16:31]
	ds_read_b64_tr_b16 v[140:141], v208 offset:0x1200
	ds_read_b64_tr_b16 v[142:143], v208 offset:0x1a00
	v_fmamk_f32 v1, v81, 0x3e0293ee, v0
	v_exp_f32_e32 v210, v1
	s_waitcnt lgkmcnt(4)
	v_mfma_f32_32x32x16_bf16 v[64:79], v[8:11], v[12:15], v[64:79]
	v_fmamk_f32 v1, v82, 0x3e0293ee, v0
	v_exp_f32_e32 v211, v1
	v_mfma_f32_32x32x16_bf16 v[48:63], v[8:11], v[132:135], v[48:63]
	s_mov_b32 m0, s97
	s_nop 0
	global_load_lds_dwordx4 v244, s[76:77]
	ds_read_b128 v[8:11], v206 offset:0x800
	ds_read_b64_tr_b16 v[12:13], v208 offset:0x1400
	ds_read_b64_tr_b16 v[14:15], v208 offset:0x1c00
	ds_read_b64_tr_b16 v[132:133], v208 offset:0x1600
	ds_read_b64_tr_b16 v[134:135], v208 offset:0x1e00
	v_fmamk_f32 v1, v83, 0x3e0293ee, v0
	v_exp_f32_e32 v212, v1
	s_waitcnt lgkmcnt(5)
	v_mfma_f32_32x32x16_bf16 v[32:47], v[4:7], v[136:139], v[32:47]
	ds_read_b64_tr_b16 v[136:137], v208 offset:0x2000
	ds_read_b64_tr_b16 v[138:139], v208 offset:0x2800
	v_fmamk_f32 v1, v84, 0x3e0293ee, v0
	v_exp_f32_e32 v213, v1
	v_mfma_f32_32x32x16_bf16 v[16:31], v[4:7], v[140:143], v[16:31]
	s_add_i32 m0, s97, 0x400
	s_nop 0
	global_load_lds_dwordx4 v245, s[76:77]
	ds_read_b64_tr_b16 v[140:141], v208 offset:0x2200
	ds_read_b64_tr_b16 v[142:143], v208 offset:0x2a00
	v_fmamk_f32 v1, v85, 0x3e0293ee, v0
	v_exp_f32_e32 v214, v1
	s_waitcnt lgkmcnt(4)
	v_mfma_f32_32x32x16_bf16 v[64:79], v[4:7], v[12:15], v[64:79]
	v_fmamk_f32 v1, v86, 0x3e0293ee, v0
	v_exp_f32_e32 v215, v1
	v_mfma_f32_32x32x16_bf16 v[48:63], v[4:7], v[132:135], v[48:63]
	s_add_i32 m0, s97, 0x4000
	s_nop 0
	global_load_lds_dwordx4 v246, s[76:77]
	ds_read_b128 v[4:7], v206 offset:0xc00
	ds_read_b64_tr_b16 v[12:13], v208 offset:0x2400
	ds_read_b64_tr_b16 v[14:15], v208 offset:0x2c00
	ds_read_b64_tr_b16 v[132:133], v208 offset:0x2600
	ds_read_b64_tr_b16 v[134:135], v208 offset:0x2e00
	v_fmamk_f32 v1, v87, 0x3e0293ee, v0
	v_exp_f32_e32 v216, v1
	s_waitcnt lgkmcnt(5)
	v_mfma_f32_32x32x16_bf16 v[32:47], v[8:11], v[136:139], v[32:47]
	ds_read_b64_tr_b16 v[136:137], v208 offset:0x3000
	ds_read_b64_tr_b16 v[138:139], v208 offset:0x3800
	v_fmamk_f32 v1, v88, 0x3e0293ee, v0
	v_exp_f32_e32 v217, v1
	v_mfma_f32_32x32x16_bf16 v[16:31], v[8:11], v[140:143], v[16:31]
	s_add_i32 m0, s97, 0x4400
	s_nop 0
	global_load_lds_dwordx4 v247, s[76:77]
	ds_read_b64_tr_b16 v[140:141], v208 offset:0x3200
	ds_read_b64_tr_b16 v[142:143], v208 offset:0x3a00
	v_fmamk_f32 v1, v89, 0x3e0293ee, v0
	v_exp_f32_e32 v218, v1
	s_waitcnt lgkmcnt(4)
	v_mfma_f32_32x32x16_bf16 v[64:79], v[8:11], v[12:15], v[64:79]
	v_fmamk_f32 v1, v90, 0x3e0293ee, v0
	v_exp_f32_e32 v219, v1
	v_mfma_f32_32x32x16_bf16 v[48:63], v[8:11], v[132:135], v[48:63]
	ds_read_b64_tr_b16 v[8:9], v208 offset:0x3400
	ds_read_b64_tr_b16 v[10:11], v208 offset:0x3c00
	ds_read_b64_tr_b16 v[12:13], v208 offset:0x3600
	ds_read_b64_tr_b16 v[14:15], v208 offset:0x3e00
	v_fmamk_f32 v1, v91, 0x3e0293ee, v0
	v_exp_f32_e32 v220, v1
	s_waitcnt lgkmcnt(4)
	v_mfma_f32_32x32x16_bf16 v[32:47], v[4:7], v[136:139], v[32:47]
	v_fmamk_f32 v1, v92, 0x3e0293ee, v0
	v_exp_f32_e32 v221, v1
	v_fmamk_f32 v1, v93, 0x3e0293ee, v0
	v_exp_f32_e32 v222, v1
	s_waitcnt lgkmcnt(0)
	v_mfma_f32_32x32x16_bf16 v[16:31], v[4:7], v[140:143], v[16:31]
	v_fmamk_f32 v1, v94, 0x3e0293ee, v0
	v_fmac_f32_e32 v0, 0x3e0293ee, v95
	v_exp_f32_e32 v223, v1
	v_exp_f32_e32 v224, v0
	v_cvt_pk_bf16_f32 v248, v209, v210
	v_cvt_pk_bf16_f32 v249, v211, v212
	v_cvt_pk_bf16_f32 v250, v213, v214
	v_cvt_pk_bf16_f32 v251, v215, v216
	v_mfma_f32_32x32x16_bf16 v[64:79], v[4:7], v[8:11], v[64:79]
	s_add_i32 s0, s88, 1
	s_nop 0
	v_permlane32_swap_b32_e32 v248, v250
	v_permlane32_swap_b32_e32 v249, v251
	ds_write_b128 v204, v[248:251]
	v_cvt_pk_bf16_f32 v248, v217, v218
	v_cvt_pk_bf16_f32 v249, v219, v220
	v_cvt_pk_bf16_f32 v250, v221, v222
	v_cvt_pk_bf16_f32 v251, v223, v224
	v_mfma_f32_32x32x16_bf16 v[48:63], v[4:7], v[12:15], v[48:63]
	s_cmp_lg_u32 s88, 2
	s_nop 0
	v_permlane32_swap_b32_e32 v248, v250
	v_permlane32_swap_b32_e32 v249, v251
	ds_write_b128 v204, v[248:251] offset:1024
	s_cselect_b32 s28, s0, 0
	s_cmp_ge_i32 s90, s80
	s_cselect_b64 s[2:3], -1, 0
	s_lshl_b32 s98, s80, 6
	s_sub_i32 s98, s98, 64
	s_min_i32 s96, s89, s98
	s_mul_i32 s96, s96, 0x6000
	s_lshl_b32 s97, s28, 15
	s_add_i32 s97, s83, s97
	v_add_u32_e32 v242, s96, v150
	v_add_u32_e32 v243, s96, v154
	v_add_u32_e32 v244, s96, v152
	v_add_u32_e32 v245, s96, v156
	v_add_u32_e32 v246, 0x100, v244
	v_add_u32_e32 v247, 0x100, v245
	s_waitcnt vmcnt(4) lgkmcnt(0)
	s_barrier

; __device__ __forceinline__ void attn_body3(const bf16* __restrict__ Qb, const bf16* __restrict__ Kh, const bf16* __restrict__ Vh,
;                                            bf16* __restrict__ Ob, int seq, int qpos0, float slS, float mraw, char* lds, const int tid) {
;     ...
;   for (int j = 0; j < NT; j += 2) { HALFSTEP(j, 0); HALFSTEP(j + 1, 1); }
.LBB0_184:
	s_waitcnt lgkmcnt(4)
	v_sub_f32_e32 v1, v1, v203
	v_add_f32_e32 v0, v207, v254
	v_mul_f32_e32 v1, 0x3e0293ee, v1
	v_mfma_f32_32x32x16_bf16 v[32:47], v[8:11], v[136:139], v[32:47]
	ds_read_b64_tr_b16 v[136:137], v208 offset:0x1000
	v_fmamk_f32 v2, v80, 0x3e0293ee, v1
	ds_read_b64_tr_b16 v[138:139], v208 offset:0x1800
	v_exp_f32_e32 v2, v2
	v_fmamk_f32 v81, v81, 0x3e0293ee, v1
	v_exp_f32_e32 v159, v81
	v_add_f32_e32 v80, 0, v2
	v_mfma_f32_32x32x16_bf16 v[16:31], v[8:11], v[140:143], v[16:31]
	ds_read_b64_tr_b16 v[140:141], v208 offset:0x1200
	ds_read_b64_tr_b16 v[142:143], v208 offset:0x1a00
	s_waitcnt lgkmcnt(4)
	v_add_f32_e32 v80, v159, v80
	v_mfma_f32_32x32x16_bf16 v[64:79], v[8:11], v[12:15], v[64:79]
	v_mfma_f32_32x32x16_bf16 v[48:63], v[8:11], v[132:135], v[48:63]
	s_mov_b32 m0, s97
	s_nop 0
	global_load_lds_dwordx4 v244, s[76:77]
	v_fmamk_f32 v8, v82, 0x3e0293ee, v1
	v_exp_f32_e32 v209, v8
	v_fmamk_f32 v9, v83, 0x3e0293ee, v1
	v_exp_f32_e32 v210, v9
	v_add_f32_e32 v8, v209, v80
	v_add_f32_e32 v132, v210, v8
	ds_read_b128 v[8:11], v202 offset:0x800
	ds_read_b64_tr_b16 v[12:13], v208 offset:0x1400
	ds_read_b64_tr_b16 v[14:15], v208 offset:0x1c00
	ds_read_b64_tr_b16 v[80:81], v208 offset:0x1600
	ds_read_b64_tr_b16 v[82:83], v208 offset:0x1e00
	s_waitcnt lgkmcnt(5)
	v_fmamk_f32 v84, v84, 0x3e0293ee, v1
	v_mfma_f32_32x32x16_bf16 v[16:31], v[4:7], v[140:143], v[16:31]
	v_exp_f32_e32 v140, v84
	v_fmamk_f32 v85, v85, 0x3e0293ee, v1
	v_exp_f32_e32 v141, v85
	v_add_f32_e32 v84, v140, v132
	ds_read_b64_tr_b16 v[132:133], v208 offset:0x2000
	ds_read_b64_tr_b16 v[134:135], v208 offset:0x2800
	v_mfma_f32_32x32x16_bf16 v[32:47], v[4:7], v[136:139], v[32:47]
	s_add_i32 m0, s97, 0x400
	s_nop 0
	global_load_lds_dwordx4 v245, s[76:77]
	ds_read_b64_tr_b16 v[136:137], v208 offset:0x2200
	ds_read_b64_tr_b16 v[138:139], v208 offset:0x2a00
	s_waitcnt lgkmcnt(4)
	v_add_f32_e32 v84, v141, v84
	v_mfma_f32_32x32x16_bf16 v[64:79], v[4:7], v[12:15], v[64:79]
	v_mfma_f32_32x32x16_bf16 v[48:63], v[4:7], v[80:83], v[48:63]
	s_add_i32 m0, s97, 0x4000
	s_nop 0
	global_load_lds_dwordx4 v246, s[76:77]
	v_fmamk_f32 v4, v86, 0x3e0293ee, v1
	v_exp_f32_e32 v142, v4
	v_fmamk_f32 v5, v87, 0x3e0293ee, v1
	v_exp_f32_e32 v143, v5
	v_add_f32_e32 v4, v142, v84
	v_add_f32_e32 v84, v143, v4
	ds_read_b128 v[4:7], v202 offset:0xc00
	ds_read_b64_tr_b16 v[12:13], v208 offset:0x2400
	ds_read_b64_tr_b16 v[14:15], v208 offset:0x2c00
	ds_read_b64_tr_b16 v[80:81], v208 offset:0x2600
	ds_read_b64_tr_b16 v[82:83], v208 offset:0x2e00
	s_waitcnt lgkmcnt(5)
	v_fmamk_f32 v85, v88, 0x3e0293ee, v1
	v_exp_f32_e32 v88, v85
	v_fmamk_f32 v85, v89, 0x3e0293ee, v1
	v_exp_f32_e32 v89, v85
	v_mfma_f32_32x32x16_bf16 v[32:47], v[8:11], v[132:135], v[32:47]
	v_add_f32_e32 v84, v88, v84
	v_mfma_f32_32x32x16_bf16 v[16:31], v[8:11], v[136:139], v[16:31]
	s_add_i32 m0, s97, 0x4400
	s_nop 0
	global_load_lds_dwordx4 v247, s[76:77]
	v_add_f32_e32 v136, v89, v84
	ds_read_b64_tr_b16 v[84:85], v208 offset:0x3000
	ds_read_b64_tr_b16 v[86:87], v208 offset:0x3800
	ds_read_b64_tr_b16 v[132:133], v208 offset:0x3200
	ds_read_b64_tr_b16 v[134:135], v208 offset:0x3a00
	s_waitcnt lgkmcnt(4)
	v_mfma_f32_32x32x16_bf16 v[64:79], v[8:11], v[12:15], v[64:79]
	v_mfma_f32_32x32x16_bf16 v[48:63], v[8:11], v[80:83], v[48:63]
	v_fmamk_f32 v8, v90, 0x3e0293ee, v1
	v_exp_f32_e32 v80, v8
	v_fmamk_f32 v9, v91, 0x3e0293ee, v1
	v_exp_f32_e32 v81, v9
	v_add_f32_e32 v8, v80, v136
	v_add_f32_e32 v82, v81, v8
	ds_read_b64_tr_b16 v[8:9], v208 offset:0x3400
	ds_read_b64_tr_b16 v[10:11], v208 offset:0x3c00
	ds_read_b64_tr_b16 v[12:13], v208 offset:0x3600
	ds_read_b64_tr_b16 v[14:15], v208 offset:0x3e00
	s_waitcnt lgkmcnt(4)
	v_mfma_f32_32x32x16_bf16 v[32:47], v[4:7], v[84:87], v[32:47]
	v_fmamk_f32 v83, v92, 0x3e0293ee, v1
	v_exp_f32_e32 v83, v83
	v_fmamk_f32 v84, v93, 0x3e0293ee, v1
	v_exp_f32_e32 v84, v84
	s_waitcnt lgkmcnt(0)
	v_add_f32_e32 v82, v83, v82
	v_add_f32_e32 v82, v84, v82
	v_mfma_f32_32x32x16_bf16 v[16:31], v[4:7], v[132:135], v[16:31]
	v_cvt_pk_bf16_f32 v248, v2, v159
	v_cvt_pk_bf16_f32 v249, v209, v210
	v_cvt_pk_bf16_f32 v250, v140, v141
	v_cvt_pk_bf16_f32 v251, v142, v143
	v_mfma_f32_32x32x16_bf16 v[64:79], v[4:7], v[8:11], v[64:79]
	s_add_i32 s0, s28, 1
	s_cmp_lg_u32 s28, 2
	s_cselect_b32 s1, s0, 0
	s_addk_i32 s89, 0x80
	s_add_i32 s90, s90, 2
	s_and_b64 vcc, exec, s[2:3]
	v_permlane32_swap_b32_e32 v248, v250
	v_permlane32_swap_b32_e32 v249, v251
	ds_write_b128 v205, v[248:251]
	v_fmamk_f32 v252, v94, 0x3e0293ee, v1
	v_exp_f32_e32 v253, v252
	v_fmac_f32_e32 v1, 0x3e0293ee, v95
	v_exp_f32_e32 v1, v1
	v_mfma_f32_32x32x16_bf16 v[48:63], v[4:7], v[12:15], v[48:63]
	v_add_f32_e32 v252, v253, v82
	v_add_f32_e32 v252, v1, v252
	v_add_f32_e32 v207, v0, v252
	v_cvt_pk_bf16_f32 v248, v88, v89
	v_cvt_pk_bf16_f32 v249, v80, v81
	v_cvt_pk_bf16_f32 v250, v83, v84
	v_cvt_pk_bf16_f32 v251, v253, v1
	s_nop 1
	v_permlane32_swap_b32_e32 v248, v250
	v_permlane32_swap_b32_e32 v249, v251
	ds_write_b128 v205, v[248:251] offset:1024
	s_waitcnt vmcnt(4) lgkmcnt(0)
	s_cbranch_vccnz .Lattn_exit
	s_mov_b32 s0, s88
	s_mov_b32 s29, s28
	s_mov_b32 s88, s1
	s_lshl_b32 s98, s80, 6
	s_sub_i32 s96, s89, 64
	s_sub_i32 s98, s98, 64
	s_min_i32 s96, s96, s98
	s_mul_i32 s96, s96, 0x6000
	s_lshl_b32 s97, s88, 15
	s_add_i32 s97, s83, s97
	v_add_u32_e32 v242, s96, v150
	v_add_u32_e32 v243, s96, v154
	v_add_u32_e32 v244, s96, v152
	v_add_u32_e32 v245, s96, v156
	v_add_u32_e32 v246, 0x100, v244
	v_add_u32_e32 v247, 0x100, v245
	s_branch .LBB0_172
.Lattn_exit:
	s_barrier
	s_branch .LBB0_187
